# P1/P7 SwiGLU epilogue: row/column dequant scale loads issued before the K-loop into spare VGPRs (v228-v254) instead of after it
# speedup vs baseline: 1.0033x; 1.0027x over previous
; template <class Epi, class Sched, bool I8 = false>
; __device__ __forceinline__ void gemm_phase(LAS unsigned char* lds, const Gemm g, const Sched& S, const Epi& E) {
;     ...
; #pragma unroll
;         for (int a = 0; a < 2; ++a)
; #pragma unroll
;             for (int b = 0; b < 2; ++b)
; #pragma unroll
;                 for (int m = 0; m < 4; ++m)
; #pragma unroll
;                     for (int n = 0; n < 2; ++n) acc[a][b][m][n] = acc_t{};
;         cur = nxt; cA = nA; cB = nB; ++ui;
;     __device__ __forceinline__ void operator()(const i32x4 (&acc)[2][2][4][2], const pg8::Unit& u, int wr, int wc, int fr, int fq) const {
;         const int row0 = u.pm * 256 + wr * 64 + fr, col0 = u.pn * 128 + wc * 32 + 8 * fq, ch0 = u.pn * 256 + wc * 32 + 8 * fq;
;         const f32x4 sg0 = *(const f32x4*)(sb + ch0), sg1 = *(const f32x4*)(sb + ch0 + 4), su0 = *(const f32x4*)(sb + ch0 + 128), su1 = *(const f32x4*)(sb + ch0 + 132);
;         float rr[2][4];
; #pragma unroll
;         for (int ai = 0; ai < 2; ++ai)
; #pragma unroll
;             for (int m = 0; m < 4; ++m) rr[ai][m] = ra[row0 + ai * 128 + m * 16];
.LBB0_1168:
	s_ashr_i32 s13, s12, 31
	s_lshl_b64 s[14:15], s[12:13], 20
	s_add_u32 s14, s28, s14
	s_addc_u32 s15, s29, s15
	s_and_b64 s[16:17], s[2:3], exec
	s_cselect_b32 s13, s15, s21
	s_cselect_b32 s49, s14, s20
	s_ashr_i32 s11, s10, 31
	s_lshl_b64 s[16:17], s[10:11], 20
	s_add_u32 s16, s30, s16
	s_addc_u32 s17, s31, s17
	s_and_b64 s[24:25], s[2:3], exec
	s_cselect_b32 s11, s17, s23
	s_cselect_b32 s50, s16, s22
	s_add_u32 s20, s20, 0xc000
	s_addc_u32 s21, s21, 0
	s_add_u32 s51, s22, 0x10000
	v_mov_b32_e32 v2, 0
	s_addc_u32 s52, s23, 0
	s_mov_b32 s53, -2
	v_mov_b32_e32 v3, v2
	v_mov_b32_e32 v4, v2
	v_mov_b32_e32 v5, v2
	v_mov_b32_e32 v6, v2
	v_mov_b32_e32 v7, v2
	v_mov_b32_e32 v8, v2
	v_mov_b32_e32 v9, v2
	v_mov_b32_e32 v18, v2
	v_mov_b32_e32 v19, v2
	v_mov_b32_e32 v20, v2
	v_mov_b32_e32 v21, v2
	v_mov_b32_e32 v22, v2
	v_mov_b32_e32 v23, v2
	v_mov_b32_e32 v24, v2
	v_mov_b32_e32 v25, v2
	v_mov_b32_e32 v34, v2
	v_mov_b32_e32 v35, v2
	v_mov_b32_e32 v36, v2
	v_mov_b32_e32 v37, v2
	v_mov_b32_e32 v38, v2
	v_mov_b32_e32 v39, v2
	v_mov_b32_e32 v40, v2
	v_mov_b32_e32 v41, v2
	v_mov_b32_e32 v50, v2
	v_mov_b32_e32 v51, v2
	v_mov_b32_e32 v52, v2
	v_mov_b32_e32 v53, v2
	v_mov_b32_e32 v54, v2
	v_mov_b32_e32 v55, v2
	v_mov_b32_e32 v56, v2
	v_mov_b32_e32 v57, v2
	v_mov_b32_e32 v10, v2
	v_mov_b32_e32 v11, v2
	v_mov_b32_e32 v12, v2
	v_mov_b32_e32 v13, v2
	v_mov_b32_e32 v14, v2
	v_mov_b32_e32 v15, v2
	v_mov_b32_e32 v16, v2
	v_mov_b32_e32 v17, v2
	v_mov_b32_e32 v26, v2
	v_mov_b32_e32 v27, v2
	v_mov_b32_e32 v28, v2
	v_mov_b32_e32 v29, v2
	v_mov_b32_e32 v30, v2
	v_mov_b32_e32 v31, v2
	v_mov_b32_e32 v32, v2
	v_mov_b32_e32 v33, v2
	v_mov_b32_e32 v42, v2
	v_mov_b32_e32 v43, v2
	v_mov_b32_e32 v44, v2
	v_mov_b32_e32 v45, v2
	v_mov_b32_e32 v46, v2
	v_mov_b32_e32 v47, v2
	v_mov_b32_e32 v48, v2
	v_mov_b32_e32 v49, v2
	v_mov_b32_e32 v58, v2
	v_mov_b32_e32 v59, v2
	v_mov_b32_e32 v60, v2
	v_mov_b32_e32 v61, v2
	v_mov_b32_e32 v62, v2
	v_mov_b32_e32 v63, v2
	v_mov_b32_e32 v64, v2
	v_mov_b32_e32 v65, v2
	v_mov_b32_e32 v66, v2
	v_mov_b32_e32 v67, v2
	v_mov_b32_e32 v68, v2
	v_mov_b32_e32 v69, v2
	v_mov_b32_e32 v70, v2
	v_mov_b32_e32 v71, v2
	v_mov_b32_e32 v72, v2
	v_mov_b32_e32 v73, v2
	v_mov_b32_e32 v82, v2
	v_mov_b32_e32 v83, v2
	v_mov_b32_e32 v84, v2
	v_mov_b32_e32 v85, v2
	v_mov_b32_e32 v86, v2
	v_mov_b32_e32 v87, v2
	v_mov_b32_e32 v88, v2
	v_mov_b32_e32 v89, v2
	v_mov_b32_e32 v106, v2
	v_mov_b32_e32 v107, v2
	v_mov_b32_e32 v108, v2
	v_mov_b32_e32 v109, v2
	v_mov_b32_e32 v110, v2
	v_mov_b32_e32 v111, v2
	v_mov_b32_e32 v112, v2
	v_mov_b32_e32 v113, v2
	v_mov_b32_e32 v122, v2
	v_mov_b32_e32 v123, v2
	v_mov_b32_e32 v124, v2
	v_mov_b32_e32 v125, v2
	v_mov_b32_e32 v126, v2
	v_mov_b32_e32 v127, v2
	v_mov_b32_e32 v128, v2
	v_mov_b32_e32 v129, v2
	v_mov_b32_e32 v74, v2
	v_mov_b32_e32 v75, v2
	v_mov_b32_e32 v76, v2
	v_mov_b32_e32 v77, v2
	v_mov_b32_e32 v78, v2
	v_mov_b32_e32 v79, v2
	v_mov_b32_e32 v80, v2
	v_mov_b32_e32 v81, v2
	v_mov_b32_e32 v94, v2
	v_mov_b32_e32 v95, v2
	v_mov_b32_e32 v96, v2
	v_mov_b32_e32 v97, v2
	v_mov_b32_e32 v102, v2
	v_mov_b32_e32 v103, v2
	v_mov_b32_e32 v104, v2
	v_mov_b32_e32 v105, v2
	v_mov_b32_e32 v114, v2
	v_mov_b32_e32 v115, v2
	v_mov_b32_e32 v116, v2
	v_mov_b32_e32 v117, v2
	v_mov_b32_e32 v118, v2
	v_mov_b32_e32 v119, v2
	v_mov_b32_e32 v120, v2
	v_mov_b32_e32 v121, v2
	v_mov_b32_e32 v130, v2
	v_mov_b32_e32 v131, v2
	v_mov_b32_e32 v132, v2
	v_mov_b32_e32 v133, v2
	v_mov_b32_e32 v134, v2
	v_mov_b32_e32 v135, v2
	v_mov_b32_e32 v136, v2
	v_mov_b32_e32 v137, v2
	s_lshl_b32 s99, s18, 8
	s_add_i32 s99, s99, s41
	v_or_b32_e32 v254, s99, v161
	v_lshl_or_b32 v253, s19, 8, v168
	v_lshlrev_b32_e32 v254, 2, v254
	v_lshlrev_b32_e32 v253, 2, v253
	global_load_dwordx4 v[228:231], v253, s[6:7]
	global_load_dwordx4 v[232:235], v253, s[6:7] offset:512
	global_load_dwordx4 v[236:239], v253, s[6:7] offset:16
	global_load_dwordx4 v[240:243], v253, s[6:7] offset:528
	global_load_dword v244, v254, s[4:5]
	global_load_dword v245, v254, s[4:5] offset:512
	global_load_dword v247, v254, s[4:5] offset:576
	global_load_dword v248, v254, s[4:5] offset:640
	global_load_dword v249, v254, s[4:5] offset:64
	global_load_dword v250, v254, s[4:5] offset:128
	global_load_dword v251, v254, s[4:5] offset:192
	global_load_dword v252, v254, s[4:5] offset:704

; __device__ __forceinline__ float silu_mul(float g, float u) { return g * u * __builtin_amdgcn_rcpf(1.0f + __builtin_amdgcn_exp2f(-g * LOG2E)); }
;     __device__ __forceinline__ void operator()(const i32x4 (&acc)[2][2][4][2], const pg8::Unit& u, int wr, int wc, int fr, int fq) const {
;         const int row0 = u.pm * 256 + wr * 64 + fr, col0 = u.pn * 128 + wc * 32 + 8 * fq, ch0 = u.pn * 256 + wc * 32 + 8 * fq;
;         const f32x4 sg0 = *(const f32x4*)(sb + ch0), sg1 = *(const f32x4*)(sb + ch0 + 4), su0 = *(const f32x4*)(sb + ch0 + 128), su1 = *(const f32x4*)(sb + ch0 + 132);
;         float rr[2][4];
; #pragma unroll
;         for (int ai = 0; ai < 2; ++ai)
; #pragma unroll
;             for (int m = 0; m < 4; ++m) rr[ai][m] = ra[row0 + ai * 128 + m * 16];
; #pragma unroll
;         for (int ai = 0; ai < 2; ++ai)
; #pragma unroll
;             for (int m = 0; m < 4; ++m) {
;                 const int row = row0 + ai * 128 + m * 16; const float r = rr[ai][m];
;                 f32x4 g0, g1, u0, u1;
; #pragma unroll
;                 for (int e = 0; e < 4; ++e) { g0[e] = (float)acc[ai][0][m][0][e] * r * sg0[e]; g1[e] = (float)acc[ai][0][m][1][e] * r * sg1[e]; u0[e] = (float)acc[ai][1][m][0][e] * r * su0[e]; u1[e] = (float)acc[ai][1][m][1][e] * r * su1[e]; }
;                 float h0 = silu_mul(g0[0], u0[0]), h1 = silu_mul(g0[1], u0[1]), h2 = silu_mul(g0[2], u0[2]), h3 = silu_mul(g0[3], u0[3]);
;                 float h4 = silu_mul(g1[0], u1[0]), h5 = silu_mul(g1[1], u1[1]), h6 = silu_mul(g1[2], u1[2]), h7 = silu_mul(g1[3], u1[3]);
.LBB0_1172:
	s_lshl_b32 s11, s18, 8
	s_add_i32 s13, s11, s41
	v_lshl_or_b32 v90, s19, 8, v168
	v_or_b32_e32 v180, s13, v161
	v_ashrrev_i32_e32 v91, 31, v90
	v_ashrrev_i32_e32 v181, 31, v180
	v_lshl_add_u64 v[90:91], v[90:91], 2, s[6:7]
	v_lshl_add_u64 v[182:183], v[180:181], 2, s[4:5]
	s_nop 0
	v_or_b32_e32 v166, 16, v180
	v_or_b32_e32 v162, 32, v180
	v_or_b32_e32 v158, 48, v180
	v_ashrrev_i32_e32 v167, 31, v166
	v_ashrrev_i32_e32 v163, 31, v162
	v_ashrrev_i32_e32 v159, 31, v158
	v_cvt_f32_i32_e32 v185, v126
	v_cvt_f32_i32_e32 v184, v134
	v_cvt_f32_i32_e32 v187, v122
	v_cvt_f32_i32_e32 v189, v127
	v_cvt_f32_i32_e32 v191, v123
	v_cvt_f32_i32_e32 v193, v128
	v_cvt_f32_i32_e32 v192, v136
	v_cvt_f32_i32_e32 v195, v124
	v_cvt_f32_i32_e32 v194, v132
	v_cvt_f32_i32_e32 v197, v129
	v_cvt_f32_i32_e32 v199, v125
	v_cvt_f32_i32_e32 v198, v133
	v_add_u32_e32 v133, 0x80, v180
	v_lshlrev_b32_e32 v123, 7, v180
	v_lshl_add_u64 v[124:125], v[166:167], 2, s[4:5]
	v_lshl_add_u64 v[126:127], v[162:163], 2, s[4:5]
	v_lshl_add_u64 v[128:129], v[158:159], 2, s[4:5]
	v_cvt_f32_i32_e32 v188, v135
	v_cvt_f32_i32_e32 v186, v130
	v_cvt_f32_i32_e32 v190, v131
	v_cvt_f32_i32_e32 v196, v137
	v_cvt_f32_i32_e32 v111, v111
	s_lshl_b32 s11, s19, 7
	s_or_b32 s11, s11, s42
	s_ashr_i32 s13, s13, 8
	v_cvt_f32_i32_e32 v113, v113
	s_ashr_i32 s11, s11, 6
	s_mulk_i32 s13, 0xac
	s_add_i32 s18, s13, s11
	s_ashr_i32 s19, s18, 31
	s_lshl_b64 s[18:19], s[18:19], 15
	s_add_u32 s18, s84, s18
	s_addc_u32 s19, s85, s19
	v_cvt_f32_i32_e32 v107, v107
	v_cvt_f32_i32_e32 v109, v109
	v_cvt_f32_i32_e32 v87, v87
	v_cvt_f32_i32_e32 v89, v89
	v_cvt_f32_i32_e32 v83, v83
	v_cvt_f32_i32_e32 v85, v85
	v_cvt_f32_i32_e32 v71, v71
	v_cvt_f32_i32_e32 v73, v73
	v_cvt_f32_i32_e32 v67, v67
	v_cvt_f32_i32_e32 v69, v69
	v_cvt_f32_i32_e32 v55, v55
	v_cvt_f32_i32_e32 v57, v57
	v_cvt_f32_i32_e32 v51, v51
	v_cvt_f32_i32_e32 v53, v53
	v_cvt_f32_i32_e32 v39, v39
	v_cvt_f32_i32_e32 v41, v41
	v_cvt_f32_i32_e32 v35, v35
	v_cvt_f32_i32_e32 v37, v37
	v_cvt_f32_i32_e32 v23, v23
	v_cvt_f32_i32_e32 v25, v25
	v_cvt_f32_i32_e32 v19, v19
	v_cvt_f32_i32_e32 v21, v21
	v_cvt_f32_i32_e32 v7, v7
	v_cvt_f32_i32_e32 v9, v9
	v_cvt_f32_i32_e32 v3, v3
	v_cvt_f32_i32_e32 v5, v5
	s_andn2_b64 vcc, exec, s[2:3]
	s_mov_b64 s[2:3], -1
	s_waitcnt vmcnt(0)
	v_mov_b32_e32 v172, v228
	v_mov_b32_e32 v173, v229
	v_mov_b32_e32 v174, v230
	v_mov_b32_e32 v175, v231
	v_mov_b32_e32 v98, v232
	v_mov_b32_e32 v99, v233
	v_mov_b32_e32 v100, v234
	v_mov_b32_e32 v101, v235
	v_mov_b32_e32 v176, v236
	v_mov_b32_e32 v177, v237
	v_mov_b32_e32 v178, v238
	v_mov_b32_e32 v179, v239
	v_mov_b32_e32 v90, v240
	v_mov_b32_e32 v91, v241
	v_mov_b32_e32 v92, v242
	v_mov_b32_e32 v93, v243
	v_mov_b32_e32 v146, v244
	v_mov_b32_e32 v136, v245
	v_mov_b32_e32 v134, v247
	v_mov_b32_e32 v132, v248
	v_mov_b32_e32 v180, v249
	v_mov_b32_e32 v164, v250
	v_mov_b32_e32 v160, v251
	v_mov_b32_e32 v122, v252
	v_mov_b32_e32 v130, v172
	v_mov_b32_e32 v131, v98
	v_mov_b32_e32 v128, v176
	v_mov_b32_e32 v129, v90
	v_mov_b32_e32 v98, v173
	v_mov_b32_e32 v90, v177
	v_pk_mul_f32 v[172:173], v[146:147], v[184:185] op_sel_hi:[0,1]
	v_pk_mul_f32 v[176:177], v[146:147], v[188:189] op_sel_hi:[0,1]
	v_pk_mul_f32 v[172:173], v[130:131], v[172:173]
	v_pk_mul_f32 v[176:177], v[98:99], v[176:177]
	v_mov_b32_e32 v126, v174
	v_mov_b32_e32 v127, v100
	v_mov_b32_e32 v124, v178
	v_mov_b32_e32 v125, v92
	v_mov_b32_e32 v100, v175
	v_mov_b32_e32 v92, v179
	v_pk_mul_f32 v[174:175], v[146:147], v[186:187] op_sel_hi:[0,1]
	v_pk_mul_f32 v[178:179], v[146:147], v[190:191] op_sel_hi:[0,1]
	v_pk_mul_f32 v[182:183], v[146:147], v[192:193] op_sel_hi:[0,1]
	v_pk_mul_f32 v[184:185], v[146:147], v[194:195] op_sel_hi:[0,1]
	v_pk_mul_f32 v[186:187], v[146:147], v[196:197] op_sel_hi:[0,1]
	v_pk_mul_f32 v[188:189], v[146:147], v[198:199] op_sel_hi:[0,1]
	v_mul_f32_e32 v137, 0xbfb8aa3b, v172
	v_mul_f32_e32 v146, 0xbfb8aa3b, v176
	v_exp_f32_e32 v137, v137
	v_exp_f32_e32 v146, v146
	v_pk_mul_f32 v[182:183], v[126:127], v[182:183]
	v_pk_mul_f32 v[186:187], v[100:101], v[186:187]
	v_add_f32_e32 v137, 1.0, v137
	v_add_f32_e32 v146, 1.0, v146
	v_rcp_f32_e32 v137, v137
	v_rcp_f32_e32 v146, v146
	v_mul_f32_e32 v159, 0xbfb8aa3b, v182
	v_mul_f32_e32 v135, v172, v173
	v_mul_f32_e32 v157, v176, v177
	v_mul_f32_e32 v163, 0xbfb8aa3b, v186
	v_exp_f32_e32 v159, v159
	v_mul_f32_e32 v135, v135, v137
	v_mul_f32_e32 v137, v157, v146
	v_exp_f32_e32 v146, v163
	v_pk_mul_f32 v[174:175], v[128:129], v[174:175]
	v_add_f32_e32 v159, 1.0, v159
	v_rcp_f32_e32 v159, v159
	v_add_f32_e32 v146, 1.0, v146
	v_mul_f32_e32 v163, 0xbfb8aa3b, v174
	v_rcp_f32_e32 v146, v146
	v_exp_f32_e32 v163, v163
	v_mul_f32_e32 v157, v182, v183
	v_mul_f32_e32 v157, v157, v159
	v_mul_f32_e32 v159, v186, v187
	v_mul_f32_e32 v146, v159, v146
	v_add_f32_e32 v159, 1.0, v163
	v_rcp_f32_e32 v159, v159
	v_pk_mul_f32 v[178:179], v[90:91], v[178:179]
	v_mul_f32_e32 v167, v174, v175
	v_mul_f32_e32 v163, 0xbfb8aa3b, v178
	v_mul_f32_e32 v159, v167, v159
	v_mul_f32_e32 v167, v178, v179
	v_cvt_f32_i32_e32 v179, v110
	v_cvt_f32_i32_e32 v110, v119
	v_exp_f32_e32 v163, v163
	v_pk_mul_f32 v[184:185], v[124:125], v[184:185]
	v_pk_mul_f32 v[188:189], v[92:93], v[188:189]
	v_pk_mul_f32 v[110:111], v[180:181], v[110:111] op_sel_hi:[0,1]
	v_add_f32_e32 v163, 1.0, v163
	v_mul_f32_e32 v172, 0xbfb8aa3b, v184
	v_pk_mul_f32 v[110:111], v[98:99], v[110:111]
	v_rcp_f32_e32 v163, v163
	v_exp_f32_e32 v172, v172
	v_mul_f32_e32 v173, 0xbfb8aa3b, v188
	v_cvt_f32_i32_e32 v119, v112
	v_cvt_f32_i32_e32 v112, v121
	v_mul_f32_e32 v121, 0xbfb8aa3b, v110
	v_exp_f32_e32 v173, v173
	v_exp_f32_e32 v121, v121
	v_mul_f32_e32 v163, v167, v163
; __host__ __device__ __forceinline__ size_t blk_off(int r, int k, int KT) { return ((size_t)((r >> 8) * KT + (k >> 6)) * 256 + (size_t)(r & 255)) * 64 + (size_t)(k & 63); }
; __device__ __forceinline__ unsigned cvt_pk_bf16(float lo, float hi) { unsigned r; asm volatile("v_cvt_pk_bf16_f32 %0, %1, %2" : "=v"(r) : "v"(lo), "v"(hi)); return r; }
;     __device__ __forceinline__ void operator()(const i32x4 (&acc)[2][2][4][2], const pg8::Unit& u, int wr, int wc, int fr, int fq) const {
;     ...
;         for (int ai = 0; ai < 2; ++ai)
; #pragma unroll
;             for (int m = 0; m < 4; ++m) {
;                 const int row = row0 + ai * 128 + m * 16; const float r = rr[ai][m];
;                 f32x4 g0, g1, u0, u1;
; #pragma unroll
;                 for (int e = 0; e < 4; ++e) { g0[e] = (float)acc[ai][0][m][0][e] * r * sg0[e]; g1[e] = (float)acc[ai][0][m][1][e] * r * sg1[e]; u0[e] = (float)acc[ai][1][m][0][e] * r * su0[e]; u1[e] = (float)acc[ai][1][m][1][e] * r * su1[e]; }
;                 float h0 = silu_mul(g0[0], u0[0]), h1 = silu_mul(g0[1], u0[1]), h2 = silu_mul(g0[2], u0[2]), h3 = silu_mul(g0[3], u0[3]);
;                 float h4 = silu_mul(g1[0], u1[0]), h5 = silu_mul(g1[1], u1[1]), h6 = silu_mul(g1[2], u1[2]), h7 = silu_mul(g1[3], u1[3]);
;                 if (ROT) {
;     ...
;                     FW_BF(h0, h1) FW_BF(h2, h3) FW_BF(h4, h5) FW_BF(h6, h7)
;                     FW_BF(h0, h2) FW_BF(h1, h3) FW_BF(h4, h6) FW_BF(h5, h7)
;                     FW_BF(h0, h4) FW_BF(h1, h5) FW_BF(h2, h6) FW_BF(h3, h7)
;     ...
;                     { const bool s16 = (fq & 1) != 0, s32 = (fq & 2) != 0;
;                       FW_X(h0, 16, s16) FW_X(h1, 16, s16) FW_X(h2, 16, s16) FW_X(h3, 16, s16) FW_X(h4, 16, s16) FW_X(h5, 16, s16) FW_X(h6, 16, s16) FW_X(h7, 16, s16)
;                       FW_X(h0, 32, s32) FW_X(h1, 32, s32) FW_X(h2, 32, s32) FW_X(h3, 32, s32) FW_X(h4, 32, s32) FW_X(h5, 32, s32) FW_X(h6, 32, s32) FW_X(h7, 32, s32) }
;     ...
;                     const float sc = 0.17677669529663687f;
;                     h0 *= sc; h1 *= sc; h2 *= sc; h3 *= sc; h4 *= sc; h5 *= sc; h6 *= sc; h7 *= sc;
;                 }
;                 u32x4 w;
;                 w.x = cvt_pk_bf16(h0, h1); w.y = cvt_pk_bf16(h2, h3); w.z = cvt_pk_bf16(h4, h5); w.w = cvt_pk_bf16(h6, h7);
;                 *(u32x4*)(O + blk_off(row, col0, KTF)) = w;
	v_add_f32_e32 v167, 1.0, v172
	v_cvt_f32_i32_e32 v178, v118
	v_cvt_f32_i32_e32 v118, v120
	v_rcp_f32_e32 v167, v167
	v_add_f32_e32 v172, 1.0, v173
	v_add_f32_e32 v121, 1.0, v121
	v_rcp_f32_e32 v172, v172
	v_rcp_f32_e32 v121, v121
	v_mul_f32_e32 v173, v184, v185
	v_pk_mul_f32 v[118:119], v[180:181], v[118:119] op_sel_hi:[0,1]
	v_pk_mul_f32 v[112:113], v[180:181], v[112:113] op_sel_hi:[0,1]
	v_mul_f32_e32 v167, v173, v167
	v_mul_f32_e32 v173, v188, v189
	v_cvt_f32_i32_e32 v183, v106
	v_cvt_f32_i32_e32 v182, v114
	v_pk_mul_f32 v[118:119], v[126:127], v[118:119]
	v_pk_mul_f32 v[112:113], v[100:101], v[112:113]
	v_mul_f32_e32 v110, v110, v111
	v_mul_f32_e32 v175, v173, v172
	v_cvt_pk_bf16_f32 v172, v135, v137
	v_cvt_pk_bf16_f32 v173, v157, v146
	v_and_b32_e32 v146, 0x6780, v123
	v_mul_f32_e32 v110, v110, v121
	v_mul_f32_e32 v111, 0xbfb8aa3b, v118
	v_mul_f32_e32 v121, 0xbfb8aa3b, v112
	v_lshl_add_u64 v[176:177], s[18:19], 0, v[146:147]
	v_mov_b32_e32 v157, v147
	v_exp_f32_e32 v111, v111
	v_exp_f32_e32 v121, v121
	v_cvt_pk_bf16_f32 v174, v159, v163
	v_cvt_pk_bf16_f32 v175, v167, v175
	v_lshl_add_u64 v[176:177], v[176:177], 0, v[156:157]
	global_store_dwordx4 v[176:177], v[172:175], off
	v_cvt_f32_i32_e32 v106, v115
	v_mul_f32_e32 v118, v118, v119
	v_pk_mul_f32 v[174:175], v[180:181], v[182:183] op_sel_hi:[0,1]
	v_pk_mul_f32 v[114:115], v[128:129], v[174:175]
	v_add_f32_e32 v111, 1.0, v111
	v_add_f32_e32 v119, 1.0, v121
	v_mul_f32_e32 v121, 0xbfb8aa3b, v114
	v_rcp_f32_e32 v111, v111
	v_exp_f32_e32 v121, v121
	v_pk_mul_f32 v[106:107], v[180:181], v[106:107] op_sel_hi:[0,1]
	v_cvt_f32_i32_e32 v175, v108
	v_cvt_f32_i32_e32 v174, v116
	v_pk_mul_f32 v[106:107], v[90:91], v[106:107]
	v_cvt_f32_i32_e32 v108, v117
	v_mul_f32_e32 v111, v118, v111
	v_mul_f32_e32 v112, v112, v113
	v_add_f32_e32 v113, 1.0, v121
	v_mul_f32_e32 v118, 0xbfb8aa3b, v106
	v_rcp_f32_e32 v113, v113
	v_exp_f32_e32 v118, v118
	v_pk_mul_f32 v[174:175], v[180:181], v[174:175] op_sel_hi:[0,1]
	v_pk_mul_f32 v[172:173], v[180:181], v[178:179] op_sel_hi:[0,1]
	v_pk_mul_f32 v[116:117], v[124:125], v[174:175]
	v_pk_mul_f32 v[108:109], v[180:181], v[108:109] op_sel_hi:[0,1]
	v_mul_f32_e32 v114, v114, v115
	v_pk_mul_f32 v[172:173], v[130:131], v[172:173]
	v_pk_mul_f32 v[108:109], v[92:93], v[108:109]
	v_mul_f32_e32 v113, v114, v113
	v_mul_f32_e32 v106, v106, v107
	v_add_f32_e32 v107, 1.0, v118
	v_mul_f32_e32 v114, 0xbfb8aa3b, v116
	v_mul_f32_e32 v120, 0xbfb8aa3b, v172
	v_rcp_f32_e32 v107, v107
	v_exp_f32_e32 v114, v114
	v_mul_f32_e32 v115, 0xbfb8aa3b, v108
	v_exp_f32_e32 v120, v120
	v_exp_f32_e32 v115, v115
	v_mul_f32_e32 v118, v106, v107
	v_add_f32_e32 v106, 1.0, v114
	v_add_f32_e32 v120, 1.0, v120
	v_rcp_f32_e32 v106, v106
	v_add_f32_e32 v107, 1.0, v115
	v_rcp_f32_e32 v120, v120
	v_rcp_f32_e32 v119, v119
	v_rcp_f32_e32 v107, v107
	v_mul_f32_e32 v114, v116, v117
	v_mul_f32_e32 v135, v172, v173
	v_mul_f32_e32 v114, v114, v106
	v_mul_f32_e32 v106, v108, v109
	v_mul_f32_e32 v120, v135, v120
	v_mul_f32_e32 v112, v112, v119
	v_mul_f32_e32 v109, v106, v107
	v_cvt_pk_bf16_f32 v106, v120, v110
	v_cvt_pk_bf16_f32 v107, v111, v112
	v_cvt_pk_bf16_f32 v108, v113, v118
	v_cvt_f32_i32_e32 v113, v86
	v_cvt_f32_i32_e32 v86, v103
	v_cvt_f32_i32_e32 v103, v88
	v_cvt_f32_i32_e32 v88, v105
	v_cvt_f32_i32_e32 v112, v102
	v_pk_mul_f32 v[86:87], v[164:165], v[86:87] op_sel_hi:[0,1]
	v_pk_mul_f32 v[86:87], v[98:99], v[86:87]
	v_cvt_f32_i32_e32 v102, v104
	v_mul_f32_e32 v105, 0xbfb8aa3b, v86
	v_exp_f32_e32 v105, v105
	v_pk_mul_f32 v[88:89], v[164:165], v[88:89] op_sel_hi:[0,1]
	v_pk_mul_f32 v[102:103], v[164:165], v[102:103] op_sel_hi:[0,1]
	v_cvt_pk_bf16_f32 v109, v114, v109
	v_add_f32_e32 v105, 1.0, v105
	v_rcp_f32_e32 v105, v105
	v_lshlrev_b32_e32 v110, 7, v166
	v_cvt_f32_i32_e32 v115, v82
	v_cvt_f32_i32_e32 v114, v94
	v_pk_mul_f32 v[102:103], v[126:127], v[102:103]
	v_pk_mul_f32 v[88:89], v[100:101], v[88:89]
	v_mul_f32_e32 v86, v86, v87
	v_and_b32_e32 v146, 0x6f80, v110
	v_mul_f32_e32 v86, v86, v105
	v_mul_f32_e32 v87, 0xbfb8aa3b, v102
	v_mul_f32_e32 v105, 0xbfb8aa3b, v88
	v_lshl_add_u64 v[110:111], s[18:19], 0, v[146:147]
	v_exp_f32_e32 v87, v87
	v_exp_f32_e32 v105, v105
	v_lshl_add_u64 v[110:111], v[110:111], 0, v[156:157]
	global_store_dwordx4 v[110:111], v[106:109], off
	v_cvt_f32_i32_e32 v82, v95
	v_mul_f32_e32 v102, v102, v103
	v_pk_mul_f32 v[108:109], v[164:165], v[114:115] op_sel_hi:[0,1]
	v_pk_mul_f32 v[94:95], v[128:129], v[108:109]
	v_add_f32_e32 v87, 1.0, v87
	v_add_f32_e32 v103, 1.0, v105
	v_mul_f32_e32 v105, 0xbfb8aa3b, v94
	v_rcp_f32_e32 v87, v87
	v_exp_f32_e32 v105, v105
	v_pk_mul_f32 v[82:83], v[164:165], v[82:83] op_sel_hi:[0,1]
	v_cvt_f32_i32_e32 v109, v84
	v_cvt_f32_i32_e32 v108, v96
	v_pk_mul_f32 v[82:83], v[90:91], v[82:83]
	v_cvt_f32_i32_e32 v84, v97
	v_mul_f32_e32 v87, v102, v87
	v_mul_f32_e32 v88, v88, v89
	v_add_f32_e32 v89, 1.0, v105
	v_mul_f32_e32 v102, 0xbfb8aa3b, v82
	v_rcp_f32_e32 v89, v89
	v_exp_f32_e32 v102, v102
	v_pk_mul_f32 v[108:109], v[164:165], v[108:109] op_sel_hi:[0,1]
	v_pk_mul_f32 v[106:107], v[164:165], v[112:113] op_sel_hi:[0,1]
	v_pk_mul_f32 v[96:97], v[124:125], v[108:109]
	v_pk_mul_f32 v[84:85], v[164:165], v[84:85] op_sel_hi:[0,1]
	v_mul_f32_e32 v94, v94, v95
	v_pk_mul_f32 v[106:107], v[130:131], v[106:107]
	v_pk_mul_f32 v[84:85], v[92:93], v[84:85]
	v_mul_f32_e32 v89, v94, v89
	v_mul_f32_e32 v82, v82, v83
	v_add_f32_e32 v83, 1.0, v102
	v_mul_f32_e32 v94, 0xbfb8aa3b, v96
	v_mul_f32_e32 v104, 0xbfb8aa3b, v106
	v_rcp_f32_e32 v83, v83
	v_exp_f32_e32 v94, v94
	v_mul_f32_e32 v95, 0xbfb8aa3b, v84
	v_exp_f32_e32 v104, v104
	v_exp_f32_e32 v95, v95
	v_mul_f32_e32 v102, v82, v83
; __host__ __device__ __forceinline__ size_t blk_off(int r, int k, int KT) { return ((size_t)((r >> 8) * KT + (k >> 6)) * 256 + (size_t)(r & 255)) * 64 + (size_t)(k & 63); }
; __device__ __forceinline__ unsigned cvt_pk_bf16(float lo, float hi) { unsigned r; asm volatile("v_cvt_pk_bf16_f32 %0, %1, %2" : "=v"(r) : "v"(lo), "v"(hi)); return r; }
;     __device__ __forceinline__ void operator()(const i32x4 (&acc)[2][2][4][2], const pg8::Unit& u, int wr, int wc, int fr, int fq) const {
;     ...
;         for (int ai = 0; ai < 2; ++ai)
; #pragma unroll
;             for (int m = 0; m < 4; ++m) {
;                 const int row = row0 + ai * 128 + m * 16; const float r = rr[ai][m];
;                 f32x4 g0, g1, u0, u1;
; #pragma unroll
;                 for (int e = 0; e < 4; ++e) { g0[e] = (float)acc[ai][0][m][0][e] * r * sg0[e]; g1[e] = (float)acc[ai][0][m][1][e] * r * sg1[e]; u0[e] = (float)acc[ai][1][m][0][e] * r * su0[e]; u1[e] = (float)acc[ai][1][m][1][e] * r * su1[e]; }
;                 float h0 = silu_mul(g0[0], u0[0]), h1 = silu_mul(g0[1], u0[1]), h2 = silu_mul(g0[2], u0[2]), h3 = silu_mul(g0[3], u0[3]);
;                 float h4 = silu_mul(g1[0], u1[0]), h5 = silu_mul(g1[1], u1[1]), h6 = silu_mul(g1[2], u1[2]), h7 = silu_mul(g1[3], u1[3]);
;                 if (ROT) {
;     ...
;                     FW_BF(h0, h1) FW_BF(h2, h3) FW_BF(h4, h5) FW_BF(h6, h7)
;                     FW_BF(h0, h2) FW_BF(h1, h3) FW_BF(h4, h6) FW_BF(h5, h7)
;                     FW_BF(h0, h4) FW_BF(h1, h5) FW_BF(h2, h6) FW_BF(h3, h7)
;     ...
;                     { const bool s16 = (fq & 1) != 0, s32 = (fq & 2) != 0;
;                       FW_X(h0, 16, s16) FW_X(h1, 16, s16) FW_X(h2, 16, s16) FW_X(h3, 16, s16) FW_X(h4, 16, s16) FW_X(h5, 16, s16) FW_X(h6, 16, s16) FW_X(h7, 16, s16)
;                       FW_X(h0, 32, s32) FW_X(h1, 32, s32) FW_X(h2, 32, s32) FW_X(h3, 32, s32) FW_X(h4, 32, s32) FW_X(h5, 32, s32) FW_X(h6, 32, s32) FW_X(h7, 32, s32) }
;     ...
;                     const float sc = 0.17677669529663687f;
;                     h0 *= sc; h1 *= sc; h2 *= sc; h3 *= sc; h4 *= sc; h5 *= sc; h6 *= sc; h7 *= sc;
;                 }
;                 u32x4 w;
;                 w.x = cvt_pk_bf16(h0, h1); w.y = cvt_pk_bf16(h2, h3); w.z = cvt_pk_bf16(h4, h5); w.w = cvt_pk_bf16(h6, h7);
;                 *(u32x4*)(O + blk_off(row, col0, KTF)) = w;
	v_add_f32_e32 v82, 1.0, v94
	v_add_f32_e32 v104, 1.0, v104
	v_rcp_f32_e32 v82, v82
	v_add_f32_e32 v83, 1.0, v95
	v_rcp_f32_e32 v104, v104
	v_rcp_f32_e32 v103, v103
	v_rcp_f32_e32 v83, v83
	v_mul_f32_e32 v94, v96, v97
	v_mul_f32_e32 v106, v106, v107
	v_mul_f32_e32 v94, v94, v82
	v_mul_f32_e32 v82, v84, v85
	v_mul_f32_e32 v104, v106, v104
	v_mul_f32_e32 v88, v88, v103
	v_mul_f32_e32 v85, v82, v83
	v_cvt_pk_bf16_f32 v82, v104, v86
	v_cvt_pk_bf16_f32 v83, v87, v88
	v_cvt_pk_bf16_f32 v84, v89, v102
	v_cvt_f32_i32_e32 v89, v70
	v_cvt_f32_i32_e32 v70, v79
	v_cvt_f32_i32_e32 v79, v72
	v_cvt_f32_i32_e32 v72, v81
	v_cvt_f32_i32_e32 v88, v78
	v_pk_mul_f32 v[70:71], v[160:161], v[70:71] op_sel_hi:[0,1]
	v_pk_mul_f32 v[70:71], v[98:99], v[70:71]
	v_cvt_f32_i32_e32 v78, v80
	v_mul_f32_e32 v81, 0xbfb8aa3b, v70
	v_exp_f32_e32 v81, v81
	v_pk_mul_f32 v[72:73], v[160:161], v[72:73] op_sel_hi:[0,1]
	v_pk_mul_f32 v[78:79], v[160:161], v[78:79] op_sel_hi:[0,1]
	v_cvt_pk_bf16_f32 v85, v94, v85
	v_add_f32_e32 v81, 1.0, v81
	v_rcp_f32_e32 v81, v81
	v_lshlrev_b32_e32 v86, 7, v162
	v_cvt_f32_i32_e32 v95, v66
	v_cvt_f32_i32_e32 v94, v74
	v_pk_mul_f32 v[78:79], v[126:127], v[78:79]
	v_pk_mul_f32 v[72:73], v[100:101], v[72:73]
	v_mul_f32_e32 v70, v70, v71
	v_and_b32_e32 v146, 0x7780, v86
	v_mul_f32_e32 v70, v70, v81
	v_mul_f32_e32 v71, 0xbfb8aa3b, v78
	v_mul_f32_e32 v81, 0xbfb8aa3b, v72
	v_lshl_add_u64 v[86:87], s[18:19], 0, v[146:147]
	v_exp_f32_e32 v71, v71
	v_exp_f32_e32 v81, v81
	v_lshl_add_u64 v[86:87], v[86:87], 0, v[156:157]
	global_store_dwordx4 v[86:87], v[82:85], off
	v_cvt_f32_i32_e32 v66, v75
	v_mul_f32_e32 v78, v78, v79
	v_pk_mul_f32 v[84:85], v[160:161], v[94:95] op_sel_hi:[0,1]
	v_pk_mul_f32 v[74:75], v[128:129], v[84:85]
	v_add_f32_e32 v71, 1.0, v71
	v_add_f32_e32 v79, 1.0, v81
	v_mul_f32_e32 v81, 0xbfb8aa3b, v74
	v_rcp_f32_e32 v71, v71
	v_exp_f32_e32 v81, v81
	v_pk_mul_f32 v[66:67], v[160:161], v[66:67] op_sel_hi:[0,1]
	v_cvt_f32_i32_e32 v85, v68
	v_cvt_f32_i32_e32 v84, v76
	v_pk_mul_f32 v[66:67], v[90:91], v[66:67]
	v_cvt_f32_i32_e32 v68, v77
	v_mul_f32_e32 v71, v78, v71
	v_mul_f32_e32 v72, v72, v73
	v_add_f32_e32 v73, 1.0, v81
	v_mul_f32_e32 v78, 0xbfb8aa3b, v66
	v_rcp_f32_e32 v73, v73
	v_exp_f32_e32 v78, v78
	v_pk_mul_f32 v[84:85], v[160:161], v[84:85] op_sel_hi:[0,1]
	v_pk_mul_f32 v[82:83], v[160:161], v[88:89] op_sel_hi:[0,1]
	v_pk_mul_f32 v[76:77], v[124:125], v[84:85]
	v_pk_mul_f32 v[68:69], v[160:161], v[68:69] op_sel_hi:[0,1]
	v_mul_f32_e32 v74, v74, v75
	v_pk_mul_f32 v[82:83], v[130:131], v[82:83]
	v_pk_mul_f32 v[68:69], v[92:93], v[68:69]
	v_mul_f32_e32 v73, v74, v73
	v_mul_f32_e32 v66, v66, v67
	v_add_f32_e32 v67, 1.0, v78
	v_mul_f32_e32 v74, 0xbfb8aa3b, v76
	v_mul_f32_e32 v80, 0xbfb8aa3b, v82
	v_rcp_f32_e32 v67, v67
	v_exp_f32_e32 v74, v74
	v_mul_f32_e32 v75, 0xbfb8aa3b, v68
	v_exp_f32_e32 v80, v80
	v_exp_f32_e32 v75, v75
	v_mul_f32_e32 v78, v66, v67
	v_add_f32_e32 v66, 1.0, v74
	v_add_f32_e32 v80, 1.0, v80
	v_rcp_f32_e32 v66, v66
	v_add_f32_e32 v67, 1.0, v75
	v_rcp_f32_e32 v80, v80
	v_rcp_f32_e32 v67, v67
	v_rcp_f32_e32 v79, v79
	v_mul_f32_e32 v74, v76, v77
	v_mul_f32_e32 v82, v82, v83
	v_mul_f32_e32 v74, v74, v66
	v_mul_f32_e32 v66, v68, v69
	v_mul_f32_e32 v80, v82, v80
	v_mul_f32_e32 v69, v66, v67
	v_cvt_pk_bf16_f32 v66, v80, v70
	v_lshlrev_b32_e32 v70, 7, v158
	v_and_b32_e32 v146, 0x7f80, v70
	v_mul_f32_e32 v72, v72, v79
	v_cvt_pk_bf16_f32 v67, v71, v72
	v_lshl_add_u64 v[70:71], s[18:19], 0, v[146:147]
	v_cvt_pk_bf16_f32 v68, v73, v78
	v_cvt_pk_bf16_f32 v69, v74, v69
	v_lshl_add_u64 v[70:71], v[70:71], 0, v[156:157]
	global_store_dwordx4 v[70:71], v[66:69], off
	v_cvt_f32_i32_e32 v71, v50
	v_cvt_f32_i32_e32 v70, v58
	v_cvt_f32_i32_e32 v69, v54
	v_cvt_f32_i32_e32 v54, v63
	v_cvt_f32_i32_e32 v63, v56
	v_cvt_f32_i32_e32 v56, v65
	v_cvt_f32_i32_e32 v68, v62
	v_pk_mul_f32 v[54:55], v[136:137], v[54:55] op_sel_hi:[0,1]
	v_pk_mul_f32 v[54:55], v[98:99], v[54:55]
	v_cvt_f32_i32_e32 v62, v64
	v_mul_f32_e32 v65, 0xbfb8aa3b, v54
	v_exp_f32_e32 v65, v65
	v_pk_mul_f32 v[56:57], v[136:137], v[56:57] op_sel_hi:[0,1]
	v_pk_mul_f32 v[62:63], v[136:137], v[62:63] op_sel_hi:[0,1]
	v_pk_mul_f32 v[62:63], v[126:127], v[62:63]
	v_add_f32_e32 v65, 1.0, v65
	v_rcp_f32_e32 v65, v65
	v_pk_mul_f32 v[56:57], v[100:101], v[56:57]
	v_mul_f32_e32 v54, v54, v55
	v_mul_f32_e32 v55, 0xbfb8aa3b, v62
	v_mul_f32_e32 v54, v54, v65
	v_mul_f32_e32 v65, 0xbfb8aa3b, v56
	v_exp_f32_e32 v55, v55
	v_exp_f32_e32 v65, v65
	v_pk_mul_f32 v[70:71], v[136:137], v[70:71] op_sel_hi:[0,1]
	v_cvt_f32_i32_e32 v50, v59
	v_pk_mul_f32 v[58:59], v[128:129], v[70:71]
	v_mul_f32_e32 v62, v62, v63
	v_add_f32_e32 v55, 1.0, v55
	v_add_f32_e32 v63, 1.0, v65
	v_mul_f32_e32 v65, 0xbfb8aa3b, v58
	v_rcp_f32_e32 v55, v55
	v_exp_f32_e32 v65, v65
	v_pk_mul_f32 v[50:51], v[136:137], v[50:51] op_sel_hi:[0,1]
	v_cvt_f32_i32_e32 v71, v52
	v_cvt_f32_i32_e32 v70, v60
	v_pk_mul_f32 v[50:51], v[90:91], v[50:51]
	v_mul_f32_e32 v55, v62, v55
	v_mul_f32_e32 v56, v56, v57
	v_add_f32_e32 v57, 1.0, v65
	v_mul_f32_e32 v62, 0xbfb8aa3b, v50
	v_rcp_f32_e32 v57, v57
	v_exp_f32_e32 v62, v62
	v_pk_mul_f32 v[70:71], v[136:137], v[70:71] op_sel_hi:[0,1]
	v_cvt_f32_i32_e32 v52, v61
	v_pk_mul_f32 v[60:61], v[124:125], v[70:71]
	v_mul_f32_e32 v58, v58, v59
	v_mul_f32_e32 v57, v58, v57
	v_mul_f32_e32 v50, v50, v51
	v_add_f32_e32 v51, 1.0, v62
	v_mul_f32_e32 v58, 0xbfb8aa3b, v60
	v_rcp_f32_e32 v51, v51
	v_exp_f32_e32 v58, v58
	v_pk_mul_f32 v[52:53], v[136:137], v[52:53] op_sel_hi:[0,1]
	v_pk_mul_f32 v[52:53], v[92:93], v[52:53]
	v_mul_f32_e32 v50, v50, v51
	v_mul_f32_e32 v59, 0xbfb8aa3b, v52
	v_exp_f32_e32 v59, v59
; __host__ __device__ __forceinline__ size_t blk_off(int r, int k, int KT) { return ((size_t)((r >> 8) * KT + (k >> 6)) * 256 + (size_t)(r & 255)) * 64 + (size_t)(k & 63); }
; __device__ __forceinline__ unsigned cvt_pk_bf16(float lo, float hi) { unsigned r; asm volatile("v_cvt_pk_bf16_f32 %0, %1, %2" : "=v"(r) : "v"(lo), "v"(hi)); return r; }
;     __device__ __forceinline__ void operator()(const i32x4 (&acc)[2][2][4][2], const pg8::Unit& u, int wr, int wc, int fr, int fq) const {
;     ...
;         for (int ai = 0; ai < 2; ++ai)
; #pragma unroll
;             for (int m = 0; m < 4; ++m) {
;                 const int row = row0 + ai * 128 + m * 16; const float r = rr[ai][m];
;                 f32x4 g0, g1, u0, u1;
; #pragma unroll
;                 for (int e = 0; e < 4; ++e) { g0[e] = (float)acc[ai][0][m][0][e] * r * sg0[e]; g1[e] = (float)acc[ai][0][m][1][e] * r * sg1[e]; u0[e] = (float)acc[ai][1][m][0][e] * r * su0[e]; u1[e] = (float)acc[ai][1][m][1][e] * r * su1[e]; }
;                 float h0 = silu_mul(g0[0], u0[0]), h1 = silu_mul(g0[1], u0[1]), h2 = silu_mul(g0[2], u0[2]), h3 = silu_mul(g0[3], u0[3]);
;                 float h4 = silu_mul(g1[0], u1[0]), h5 = silu_mul(g1[1], u1[1]), h6 = silu_mul(g1[2], u1[2]), h7 = silu_mul(g1[3], u1[3]);
;                 if (ROT) {
;     ...
;                     FW_BF(h0, h1) FW_BF(h2, h3) FW_BF(h4, h5) FW_BF(h6, h7)
;                     FW_BF(h0, h2) FW_BF(h1, h3) FW_BF(h4, h6) FW_BF(h5, h7)
;                     FW_BF(h0, h4) FW_BF(h1, h5) FW_BF(h2, h6) FW_BF(h3, h7)
;     ...
;                     { const bool s16 = (fq & 1) != 0, s32 = (fq & 2) != 0;
;                       FW_X(h0, 16, s16) FW_X(h1, 16, s16) FW_X(h2, 16, s16) FW_X(h3, 16, s16) FW_X(h4, 16, s16) FW_X(h5, 16, s16) FW_X(h6, 16, s16) FW_X(h7, 16, s16)
;                       FW_X(h0, 32, s32) FW_X(h1, 32, s32) FW_X(h2, 32, s32) FW_X(h3, 32, s32) FW_X(h4, 32, s32) FW_X(h5, 32, s32) FW_X(h6, 32, s32) FW_X(h7, 32, s32) }
;     ...
;                     const float sc = 0.17677669529663687f;
;                     h0 *= sc; h1 *= sc; h2 *= sc; h3 *= sc; h4 *= sc; h5 *= sc; h6 *= sc; h7 *= sc;
;                 }
;                 u32x4 w;
;                 w.x = cvt_pk_bf16(h0, h1); w.y = cvt_pk_bf16(h2, h3); w.z = cvt_pk_bf16(h4, h5); w.w = cvt_pk_bf16(h6, h7);
;                 *(u32x4*)(O + blk_off(row, col0, KTF)) = w;
	v_add_f32_e32 v51, 1.0, v58
	v_rcp_f32_e32 v51, v51
	v_pk_mul_f32 v[68:69], v[136:137], v[68:69] op_sel_hi:[0,1]
	v_pk_mul_f32 v[68:69], v[130:131], v[68:69]
	v_add_f32_e32 v58, 1.0, v59
	v_mul_f32_e32 v59, v60, v61
	v_mul_f32_e32 v64, 0xbfb8aa3b, v68
	v_mul_f32_e32 v51, v59, v51
	v_cvt_f32_i32_e32 v59, v38
	v_cvt_f32_i32_e32 v38, v47
	v_exp_f32_e32 v64, v64
	v_rcp_f32_e32 v58, v58
	v_rcp_f32_e32 v63, v63
	v_pk_mul_f32 v[38:39], v[134:135], v[38:39] op_sel_hi:[0,1]
	v_add_f32_e32 v64, 1.0, v64
	v_pk_mul_f32 v[38:39], v[98:99], v[38:39]
	v_rcp_f32_e32 v64, v64
	v_cvt_f32_i32_e32 v47, v40
	v_cvt_f32_i32_e32 v40, v49
	v_mul_f32_e32 v49, 0xbfb8aa3b, v38
	v_exp_f32_e32 v49, v49
	v_mul_f32_e32 v52, v52, v53
	v_mul_f32_e32 v68, v68, v69
	v_mul_f32_e32 v58, v52, v58
	v_mul_f32_e32 v64, v68, v64
	v_mul_f32_e32 v56, v56, v63
	v_cvt_pk_bf16_f32 v52, v64, v54
	v_cvt_pk_bf16_f32 v53, v55, v56
	v_cvt_pk_bf16_f32 v54, v57, v50
	v_cvt_pk_bf16_f32 v55, v51, v58
	v_cvt_f32_i32_e32 v58, v46
	v_cvt_f32_i32_e32 v46, v48
	v_add_f32_e32 v49, 1.0, v49
	v_lshrrev_b32_e32 v66, 8, v133
	v_mov_b32_e32 v67, s11
	v_rcp_f32_e32 v49, v49
	v_mad_i32_i24 v66, v66, s48, v67
	v_ashrrev_i32_e32 v67, 31, v66
	v_pk_mul_f32 v[46:47], v[134:135], v[46:47] op_sel_hi:[0,1]
	v_pk_mul_f32 v[40:41], v[134:135], v[40:41] op_sel_hi:[0,1]
	v_lshlrev_b64 v[66:67], 15, v[66:67]
	v_lshlrev_b32_e32 v56, 7, v133
	v_cvt_f32_i32_e32 v61, v34
	v_cvt_f32_i32_e32 v60, v42
	v_pk_mul_f32 v[46:47], v[126:127], v[46:47]
	v_pk_mul_f32 v[40:41], v[100:101], v[40:41]
	v_mul_f32_e32 v38, v38, v39
	v_lshl_add_u64 v[50:51], s[84:85], 0, v[66:67]
	v_and_b32_e32 v146, 0x6780, v56
	v_mul_f32_e32 v38, v38, v49
	v_mul_f32_e32 v39, 0xbfb8aa3b, v46
	v_mul_f32_e32 v49, 0xbfb8aa3b, v40
	v_lshl_add_u64 v[56:57], v[50:51], 0, v[146:147]
	v_exp_f32_e32 v39, v39
	v_exp_f32_e32 v49, v49
	v_lshl_add_u64 v[56:57], v[56:57], 0, v[156:157]
	global_store_dwordx4 v[56:57], v[52:55], off
	v_cvt_f32_i32_e32 v34, v43
	v_mul_f32_e32 v46, v46, v47
	v_pk_mul_f32 v[54:55], v[134:135], v[60:61] op_sel_hi:[0,1]
	v_pk_mul_f32 v[42:43], v[128:129], v[54:55]
	v_add_f32_e32 v39, 1.0, v39
	v_add_f32_e32 v47, 1.0, v49
	v_mul_f32_e32 v49, 0xbfb8aa3b, v42
	v_rcp_f32_e32 v39, v39
	v_exp_f32_e32 v49, v49
	v_pk_mul_f32 v[34:35], v[134:135], v[34:35] op_sel_hi:[0,1]
	v_cvt_f32_i32_e32 v55, v36
	v_cvt_f32_i32_e32 v54, v44
	v_pk_mul_f32 v[34:35], v[90:91], v[34:35]
	v_cvt_f32_i32_e32 v36, v45
	v_mul_f32_e32 v39, v46, v39
	v_mul_f32_e32 v40, v40, v41
	v_add_f32_e32 v41, 1.0, v49
	v_mul_f32_e32 v46, 0xbfb8aa3b, v34
	v_rcp_f32_e32 v41, v41
	v_exp_f32_e32 v46, v46
	v_pk_mul_f32 v[54:55], v[134:135], v[54:55] op_sel_hi:[0,1]
	v_pk_mul_f32 v[52:53], v[134:135], v[58:59] op_sel_hi:[0,1]
	v_pk_mul_f32 v[44:45], v[124:125], v[54:55]
	v_pk_mul_f32 v[36:37], v[134:135], v[36:37] op_sel_hi:[0,1]
	v_mul_f32_e32 v42, v42, v43
	v_pk_mul_f32 v[52:53], v[130:131], v[52:53]
	v_pk_mul_f32 v[36:37], v[92:93], v[36:37]
	v_mul_f32_e32 v41, v42, v41
	v_mul_f32_e32 v34, v34, v35
	v_add_f32_e32 v35, 1.0, v46
	v_mul_f32_e32 v42, 0xbfb8aa3b, v44
	v_mul_f32_e32 v48, 0xbfb8aa3b, v52
	v_rcp_f32_e32 v35, v35
	v_exp_f32_e32 v42, v42
	v_mul_f32_e32 v43, 0xbfb8aa3b, v36
	v_exp_f32_e32 v48, v48
	v_exp_f32_e32 v43, v43
	v_mul_f32_e32 v46, v34, v35
	v_add_f32_e32 v34, 1.0, v42
	v_add_f32_e32 v48, 1.0, v48
	v_rcp_f32_e32 v34, v34
	v_add_f32_e32 v35, 1.0, v43
	v_rcp_f32_e32 v48, v48
	v_rcp_f32_e32 v47, v47
	v_rcp_f32_e32 v35, v35
	v_mul_f32_e32 v42, v44, v45
	v_mul_f32_e32 v52, v52, v53
	v_mul_f32_e32 v42, v42, v34
	v_mul_f32_e32 v34, v36, v37
	v_mul_f32_e32 v48, v52, v48
	v_mul_f32_e32 v40, v40, v47
	v_mul_f32_e32 v37, v34, v35
	v_cvt_pk_bf16_f32 v34, v48, v38
	v_cvt_pk_bf16_f32 v35, v39, v40
	v_cvt_pk_bf16_f32 v36, v41, v46
	v_cvt_f32_i32_e32 v41, v22
	v_cvt_f32_i32_e32 v22, v31
	v_cvt_f32_i32_e32 v31, v24
	v_cvt_f32_i32_e32 v24, v33
	v_cvt_f32_i32_e32 v40, v30
	v_pk_mul_f32 v[22:23], v[132:133], v[22:23] op_sel_hi:[0,1]
	v_pk_mul_f32 v[22:23], v[98:99], v[22:23]
	v_cvt_f32_i32_e32 v30, v32
	v_mul_f32_e32 v33, 0xbfb8aa3b, v22
	v_exp_f32_e32 v33, v33
	v_pk_mul_f32 v[24:25], v[132:133], v[24:25] op_sel_hi:[0,1]
	v_pk_mul_f32 v[30:31], v[132:133], v[30:31] op_sel_hi:[0,1]
	v_cvt_pk_bf16_f32 v37, v42, v37
	v_add_f32_e32 v33, 1.0, v33
	v_rcp_f32_e32 v33, v33
	v_add_u32_e32 v38, 0x4800, v123
	v_cvt_f32_i32_e32 v43, v18
	v_cvt_f32_i32_e32 v42, v26
	v_pk_mul_f32 v[30:31], v[126:127], v[30:31]
	v_pk_mul_f32 v[24:25], v[100:101], v[24:25]
	v_mul_f32_e32 v22, v22, v23
	v_and_b32_e32 v146, 0x6f80, v38
	v_mul_f32_e32 v22, v22, v33
	v_mul_f32_e32 v23, 0xbfb8aa3b, v30
	v_mul_f32_e32 v33, 0xbfb8aa3b, v24
	v_lshl_add_u64 v[38:39], v[50:51], 0, v[146:147]
	v_exp_f32_e32 v23, v23
	v_exp_f32_e32 v33, v33
	v_lshl_add_u64 v[38:39], v[38:39], 0, v[156:157]
	global_store_dwordx4 v[38:39], v[34:37], off
	v_cvt_f32_i32_e32 v18, v27
	v_mul_f32_e32 v30, v30, v31
; template <class Epi, class Sched, bool I8 = false>
; __device__ __forceinline__ void gemm_phase(LAS unsigned char* lds, const Gemm g, const Sched& S, const Epi& E) {
;     ...
;         if (!has_next) break;
; #pragma unroll
;         for (int a = 0; a < 2; ++a)
; #pragma unroll
;             for (int b = 0; b < 2; ++b)
; #pragma unroll
;                 for (int m = 0; m < 4; ++m)
; #pragma unroll
;     __device__ __forceinline__ void operator()(const i32x4 (&acc)[2][2][4][2], const pg8::Unit& u, int wr, int wc, int fr, int fq) const {
;     ...
;         for (int ai = 0; ai < 2; ++ai)
; #pragma unroll
;             for (int m = 0; m < 4; ++m) {
;                 const int row = row0 + ai * 128 + m * 16; const float r = rr[ai][m];
;                 f32x4 g0, g1, u0, u1;
; #pragma unroll
;                 for (int e = 0; e < 4; ++e) { g0[e] = (float)acc[ai][0][m][0][e] * r * sg0[e]; g1[e] = (float)acc[ai][0][m][1][e] * r * sg1[e]; u0[e] = (float)acc[ai][1][m][0][e] * r * su0[e]; u1[e] = (float)acc[ai][1][m][1][e] * r * su1[e]; }
;                 float h0 = silu_mul(g0[0], u0[0]), h1 = silu_mul(g0[1], u0[1]), h2 = silu_mul(g0[2], u0[2]), h3 = silu_mul(g0[3], u0[3]);
;                 float h4 = silu_mul(g1[0], u1[0]), h5 = silu_mul(g1[1], u1[1]), h6 = silu_mul(g1[2], u1[2]), h7 = silu_mul(g1[3], u1[3]);
;                 if (ROT) {
;     ...
;                     FW_BF(h0, h1) FW_BF(h2, h3) FW_BF(h4, h5) FW_BF(h6, h7)
;                     FW_BF(h0, h2) FW_BF(h1, h3) FW_BF(h4, h6) FW_BF(h5, h7)
;                     FW_BF(h0, h4) FW_BF(h1, h5) FW_BF(h2, h6) FW_BF(h3, h7)
;     ...
;                     { const bool s16 = (fq & 1) != 0, s32 = (fq & 2) != 0;
;                       FW_X(h0, 16, s16) FW_X(h1, 16, s16) FW_X(h2, 16, s16) FW_X(h3, 16, s16) FW_X(h4, 16, s16) FW_X(h5, 16, s16) FW_X(h6, 16, s16) FW_X(h7, 16, s16)
;                       FW_X(h0, 32, s32) FW_X(h1, 32, s32) FW_X(h2, 32, s32) FW_X(h3, 32, s32) FW_X(h4, 32, s32) FW_X(h5, 32, s32) FW_X(h6, 32, s32) FW_X(h7, 32, s32) }
;     ...
;                     const float sc = 0.17677669529663687f;
;                     h0 *= sc; h1 *= sc; h2 *= sc; h3 *= sc; h4 *= sc; h5 *= sc; h6 *= sc; h7 *= sc;
;                 }
;                 u32x4 w;
;                 w.x = cvt_pk_bf16(h0, h1); w.y = cvt_pk_bf16(h2, h3); w.z = cvt_pk_bf16(h4, h5); w.w = cvt_pk_bf16(h6, h7);
;                 *(u32x4*)(O + blk_off(row, col0, KTF)) = w;
	v_pk_mul_f32 v[36:37], v[132:133], v[42:43] op_sel_hi:[0,1]
	v_pk_mul_f32 v[26:27], v[128:129], v[36:37]
	v_add_f32_e32 v23, 1.0, v23
	v_add_f32_e32 v31, 1.0, v33
	v_mul_f32_e32 v33, 0xbfb8aa3b, v26
	v_rcp_f32_e32 v23, v23
	v_exp_f32_e32 v33, v33
	v_pk_mul_f32 v[18:19], v[132:133], v[18:19] op_sel_hi:[0,1]
	v_cvt_f32_i32_e32 v37, v20
	v_cvt_f32_i32_e32 v36, v28
	v_pk_mul_f32 v[18:19], v[90:91], v[18:19]
	v_cvt_f32_i32_e32 v20, v29
	v_mul_f32_e32 v23, v30, v23
	v_mul_f32_e32 v24, v24, v25
	v_add_f32_e32 v25, 1.0, v33
	v_mul_f32_e32 v30, 0xbfb8aa3b, v18
	v_rcp_f32_e32 v25, v25
	v_exp_f32_e32 v30, v30
	v_pk_mul_f32 v[36:37], v[132:133], v[36:37] op_sel_hi:[0,1]
	v_pk_mul_f32 v[34:35], v[132:133], v[40:41] op_sel_hi:[0,1]
	v_pk_mul_f32 v[28:29], v[124:125], v[36:37]
	v_pk_mul_f32 v[20:21], v[132:133], v[20:21] op_sel_hi:[0,1]
	v_mul_f32_e32 v26, v26, v27
	v_pk_mul_f32 v[34:35], v[130:131], v[34:35]
	v_pk_mul_f32 v[20:21], v[92:93], v[20:21]
	v_mul_f32_e32 v25, v26, v25
	v_mul_f32_e32 v18, v18, v19
	v_add_f32_e32 v19, 1.0, v30
	v_mul_f32_e32 v26, 0xbfb8aa3b, v28
	v_mul_f32_e32 v32, 0xbfb8aa3b, v34
	v_rcp_f32_e32 v19, v19
	v_exp_f32_e32 v26, v26
	v_mul_f32_e32 v27, 0xbfb8aa3b, v20
	v_exp_f32_e32 v32, v32
	v_exp_f32_e32 v27, v27
	v_mul_f32_e32 v30, v18, v19
	v_add_f32_e32 v18, 1.0, v26
	v_add_f32_e32 v32, 1.0, v32
	v_rcp_f32_e32 v18, v18
	v_add_f32_e32 v19, 1.0, v27
	v_rcp_f32_e32 v32, v32
	v_rcp_f32_e32 v31, v31
	v_rcp_f32_e32 v19, v19
	v_mul_f32_e32 v26, v28, v29
	v_mul_f32_e32 v34, v34, v35
	v_mul_f32_e32 v26, v26, v18
	v_mul_f32_e32 v18, v20, v21
	v_mul_f32_e32 v32, v34, v32
	v_mul_f32_e32 v24, v24, v31
	v_mul_f32_e32 v21, v18, v19
	v_cvt_pk_bf16_f32 v18, v32, v22
	v_cvt_pk_bf16_f32 v19, v23, v24
	v_cvt_pk_bf16_f32 v20, v25, v30
	v_cvt_f32_i32_e32 v25, v6
	v_cvt_f32_i32_e32 v6, v15
	v_cvt_f32_i32_e32 v15, v8
	v_cvt_f32_i32_e32 v8, v17
	v_cvt_f32_i32_e32 v24, v14
	v_pk_mul_f32 v[6:7], v[122:123], v[6:7] op_sel_hi:[0,1]
	v_pk_mul_f32 v[6:7], v[98:99], v[6:7]
	v_cvt_f32_i32_e32 v14, v16
	v_mul_f32_e32 v17, 0xbfb8aa3b, v6
	v_exp_f32_e32 v17, v17
	v_pk_mul_f32 v[8:9], v[122:123], v[8:9] op_sel_hi:[0,1]
	v_pk_mul_f32 v[14:15], v[122:123], v[14:15] op_sel_hi:[0,1]
	v_cvt_pk_bf16_f32 v21, v26, v21
	v_add_f32_e32 v17, 1.0, v17
	v_rcp_f32_e32 v17, v17
	v_add_u32_e32 v22, 0x5000, v123
	v_cvt_f32_i32_e32 v27, v2
	v_cvt_f32_i32_e32 v26, v10
	v_pk_mul_f32 v[14:15], v[126:127], v[14:15]
	v_pk_mul_f32 v[8:9], v[100:101], v[8:9]
	v_mul_f32_e32 v6, v6, v7
	v_and_b32_e32 v146, 0x7780, v22
	v_mul_f32_e32 v6, v6, v17
	v_mul_f32_e32 v7, 0xbfb8aa3b, v14
	v_mul_f32_e32 v17, 0xbfb8aa3b, v8
	v_lshl_add_u64 v[22:23], v[50:51], 0, v[146:147]
	v_exp_f32_e32 v7, v7
	v_exp_f32_e32 v17, v17
	v_lshl_add_u64 v[22:23], v[22:23], 0, v[156:157]
	global_store_dwordx4 v[22:23], v[18:21], off
	v_cvt_f32_i32_e32 v2, v11
	v_mul_f32_e32 v14, v14, v15
	v_pk_mul_f32 v[20:21], v[122:123], v[26:27] op_sel_hi:[0,1]
	v_pk_mul_f32 v[10:11], v[128:129], v[20:21]
	v_add_f32_e32 v7, 1.0, v7
	v_add_f32_e32 v15, 1.0, v17
	v_mul_f32_e32 v17, 0xbfb8aa3b, v10
	v_rcp_f32_e32 v7, v7
	v_exp_f32_e32 v17, v17
	v_pk_mul_f32 v[2:3], v[122:123], v[2:3] op_sel_hi:[0,1]
	v_cvt_f32_i32_e32 v21, v4
	v_cvt_f32_i32_e32 v20, v12
	v_pk_mul_f32 v[2:3], v[90:91], v[2:3]
	v_cvt_f32_i32_e32 v4, v13
	v_mul_f32_e32 v7, v14, v7
	v_mul_f32_e32 v8, v8, v9
	v_add_f32_e32 v9, 1.0, v17
	v_mul_f32_e32 v14, 0xbfb8aa3b, v2
	v_rcp_f32_e32 v9, v9
	v_exp_f32_e32 v14, v14
	v_pk_mul_f32 v[20:21], v[122:123], v[20:21] op_sel_hi:[0,1]
	v_pk_mul_f32 v[18:19], v[122:123], v[24:25] op_sel_hi:[0,1]
	v_pk_mul_f32 v[12:13], v[124:125], v[20:21]
	v_pk_mul_f32 v[4:5], v[122:123], v[4:5] op_sel_hi:[0,1]
	v_mul_f32_e32 v10, v10, v11
	v_pk_mul_f32 v[18:19], v[130:131], v[18:19]
	v_pk_mul_f32 v[4:5], v[92:93], v[4:5]
	v_mul_f32_e32 v9, v10, v9
	v_mul_f32_e32 v2, v2, v3
	v_add_f32_e32 v3, 1.0, v14
	v_mul_f32_e32 v10, 0xbfb8aa3b, v12
	v_mul_f32_e32 v16, 0xbfb8aa3b, v18
	v_rcp_f32_e32 v3, v3
	v_exp_f32_e32 v10, v10
	v_mul_f32_e32 v11, 0xbfb8aa3b, v4
	v_exp_f32_e32 v16, v16
	v_exp_f32_e32 v11, v11
	v_mul_f32_e32 v14, v2, v3
	v_add_f32_e32 v2, 1.0, v10
	v_add_f32_e32 v16, 1.0, v16
	v_rcp_f32_e32 v2, v2
	v_add_f32_e32 v3, 1.0, v11
	v_rcp_f32_e32 v16, v16
	v_rcp_f32_e32 v3, v3
	v_rcp_f32_e32 v15, v15
	v_mul_f32_e32 v10, v12, v13
	v_mul_f32_e32 v18, v18, v19
	v_mul_f32_e32 v10, v10, v2
	v_mul_f32_e32 v2, v4, v5
	v_mul_f32_e32 v16, v18, v16
	v_mul_f32_e32 v5, v2, v3
	v_cvt_pk_bf16_f32 v2, v16, v6
	v_add_u32_e32 v6, 0x5800, v123
	v_and_b32_e32 v146, 0x7f80, v6
	v_mul_f32_e32 v8, v8, v15
	v_cvt_pk_bf16_f32 v3, v7, v8
	v_lshl_add_u64 v[6:7], v[50:51], 0, v[146:147]
	v_lshl_add_u64 v[6:7], v[6:7], 0, v[156:157]
	v_cvt_pk_bf16_f32 v4, v9, v14
	v_cvt_pk_bf16_f32 v5, v10, v5
	global_store_dwordx4 v[6:7], v[2:5], off
	s_cbranch_vccnz .LBB0_1165
	s_andn2_b64 vcc, exec, s[0:1]
	s_cbranch_vccnz .LBB0_1164
	s_barrier
	s_branch .LBB0_1164
